# sc1 (device-scope write-through) on P6 hidden-activation stores so the barrier release flush has less dirty L2
# speedup vs baseline: 1.0031x; 1.0031x over previous
.LBB0_667:
	v_lshl_add_u32 v222, s77, 8, v154
	v_lshlrev_b32_e32 v223, 2, v222
	s_lshl_b32 s14, s77, 21
	s_lshl_b32 s15, s76, 13
	s_add_i32 s14, s14, s15
	v_and_b32_e32 v224, 15, v165
	v_lshlrev_b32_e32 v224, 6, v224
	v_and_b32_e32 v225, 0x30, v165
	v_or_b32_e32 v224, v224, v225
	v_and_b32_e32 v225, 8, v165
	v_lshlrev_b32_e32 v225, 2, v225
	v_xor_b32_e32 v224, v224, v225
	v_and_b32_e32 v225, 0xc0, v165
	v_lshl_or_b32 v224, v225, 4, v224
	v_and_b32_e32 v225, 0x100, v165
	v_lshl_or_b32 v224, v225, 11, v224
	v_add_u32_e32 v224, s14, v224
	v_add_u32_e32 v226, 0x1000, v224
	global_load_dword v166, v223, s[6:7]
	global_load_dword v168, v223, s[6:7] offset:64
	global_load_dword v170, v223, s[6:7] offset:128
	global_load_dword v172, v223, s[6:7] offset:192
	global_load_dword v174, v223, s[6:7] offset:512
	global_load_dword v176, v223, s[6:7] offset:576
	global_load_dword v178, v223, s[6:7] offset:640
	global_load_dword v180, v223, s[6:7] offset:704
	s_waitcnt vmcnt(7)
	v_fmamk_f32 v166, v166, 0x3a800000, v148
	v_rsq_f32_e32 v166, v166
	s_nop 0
	v_pk_mul_f32 v[124:125], v[124:125], v[166:167] op_sel_hi:[1,0]
	v_pk_mul_f32 v[126:127], v[126:127], v[166:167] op_sel_hi:[1,0]
	v_pk_mul_f32 v[120:121], v[120:121], v[166:167] op_sel_hi:[1,0]
	v_pk_mul_f32 v[122:123], v[122:123], v[166:167] op_sel_hi:[1,0]
	v_pk_mul_f32 v[116:117], v[116:117], v[166:167] op_sel_hi:[1,0]
	v_pk_mul_f32 v[118:119], v[118:119], v[166:167] op_sel_hi:[1,0]
	v_pk_mul_f32 v[112:113], v[112:113], v[166:167] op_sel_hi:[1,0]
	v_pk_mul_f32 v[114:115], v[114:115], v[166:167] op_sel_hi:[1,0]
	v_max_f32_e32 v124, 0, v124
	v_max_f32_e32 v125, 0, v125
	v_max_f32_e32 v126, 0, v126
	v_max_f32_e32 v127, 0, v127
	v_max_f32_e32 v120, 0, v120
	v_max_f32_e32 v121, 0, v121
	v_max_f32_e32 v122, 0, v122
	v_max_f32_e32 v123, 0, v123
	v_max_f32_e32 v116, 0, v116
	v_max_f32_e32 v117, 0, v117
	v_max_f32_e32 v118, 0, v118
	v_max_f32_e32 v119, 0, v119
	v_max_f32_e32 v112, 0, v112
	v_max_f32_e32 v113, 0, v113
	v_max_f32_e32 v114, 0, v114
	v_max_f32_e32 v115, 0, v115
	v_pk_mul_f32 v[124:125], v[124:125], v[124:125]
	v_pk_mul_f32 v[126:127], v[126:127], v[126:127]
	v_pk_mul_f32 v[120:121], v[120:121], v[120:121]
	v_pk_mul_f32 v[122:123], v[122:123], v[122:123]
	v_pk_mul_f32 v[116:117], v[116:117], v[116:117]
	v_pk_mul_f32 v[118:119], v[118:119], v[118:119]
	v_pk_mul_f32 v[112:113], v[112:113], v[112:113]
	v_pk_mul_f32 v[114:115], v[114:115], v[114:115]
	v_cvt_pk_bf16_f32 v124, v124, v125
	v_cvt_pk_bf16_f32 v125, v126, v127
	v_cvt_pk_bf16_f32 v126, v120, v121
	v_cvt_pk_bf16_f32 v127, v122, v123
	v_cvt_pk_bf16_f32 v116, v116, v117
	v_cvt_pk_bf16_f32 v117, v118, v119
	v_cvt_pk_bf16_f32 v118, v112, v113
	v_cvt_pk_bf16_f32 v119, v114, v115
	global_store_dwordx4 v224, v[124:127], s[48:49] sc1
	global_store_dwordx4 v226, v[116:119], s[48:49] sc1
	s_waitcnt vmcnt(8)
	v_fmamk_f32 v168, v168, 0x3a800000, v148
	v_rsq_f32_e32 v168, v168
	s_nop 0
	v_pk_mul_f32 v[108:109], v[108:109], v[168:169] op_sel_hi:[1,0]
	v_pk_mul_f32 v[110:111], v[110:111], v[168:169] op_sel_hi:[1,0]
	v_pk_mul_f32 v[104:105], v[104:105], v[168:169] op_sel_hi:[1,0]
	v_pk_mul_f32 v[106:107], v[106:107], v[168:169] op_sel_hi:[1,0]
	v_pk_mul_f32 v[100:101], v[100:101], v[168:169] op_sel_hi:[1,0]
	v_pk_mul_f32 v[102:103], v[102:103], v[168:169] op_sel_hi:[1,0]
	v_pk_mul_f32 v[96:97], v[96:97], v[168:169] op_sel_hi:[1,0]
	v_pk_mul_f32 v[98:99], v[98:99], v[168:169] op_sel_hi:[1,0]
	v_max_f32_e32 v108, 0, v108
	v_max_f32_e32 v109, 0, v109
	v_max_f32_e32 v110, 0, v110
	v_max_f32_e32 v111, 0, v111
	v_max_f32_e32 v104, 0, v104
	v_max_f32_e32 v105, 0, v105
	v_max_f32_e32 v106, 0, v106
	v_max_f32_e32 v107, 0, v107
	v_max_f32_e32 v100, 0, v100
	v_max_f32_e32 v101, 0, v101
	v_max_f32_e32 v102, 0, v102
	v_max_f32_e32 v103, 0, v103
	v_max_f32_e32 v96, 0, v96
	v_max_f32_e32 v97, 0, v97
	v_max_f32_e32 v98, 0, v98
	v_max_f32_e32 v99, 0, v99
	v_pk_mul_f32 v[108:109], v[108:109], v[108:109]
	v_pk_mul_f32 v[110:111], v[110:111], v[110:111]
	v_pk_mul_f32 v[104:105], v[104:105], v[104:105]
	v_pk_mul_f32 v[106:107], v[106:107], v[106:107]
	v_pk_mul_f32 v[100:101], v[100:101], v[100:101]
	v_pk_mul_f32 v[102:103], v[102:103], v[102:103]
	v_pk_mul_f32 v[96:97], v[96:97], v[96:97]
	v_pk_mul_f32 v[98:99], v[98:99], v[98:99]
	v_cvt_pk_bf16_f32 v108, v108, v109
	v_cvt_pk_bf16_f32 v109, v110, v111
	v_cvt_pk_bf16_f32 v110, v104, v105
	v_cvt_pk_bf16_f32 v111, v106, v107
	v_cvt_pk_bf16_f32 v100, v100, v101
	v_cvt_pk_bf16_f32 v101, v102, v103
	v_cvt_pk_bf16_f32 v102, v96, v97
	v_cvt_pk_bf16_f32 v103, v98, v99
	v_add_u32_e32 v225, 0x20000, v224
	v_add_u32_e32 v227, 0x20000, v226
	global_store_dwordx4 v225, v[108:111], s[48:49] sc1
	global_store_dwordx4 v227, v[100:103], s[48:49] sc1
	s_waitcnt vmcnt(9)
	v_fmamk_f32 v170, v170, 0x3a800000, v148
	v_rsq_f32_e32 v170, v170
	s_nop 0
	v_pk_mul_f32 v[92:93], v[92:93], v[170:171] op_sel_hi:[1,0]
	v_pk_mul_f32 v[94:95], v[94:95], v[170:171] op_sel_hi:[1,0]
	v_pk_mul_f32 v[88:89], v[88:89], v[170:171] op_sel_hi:[1,0]
	v_pk_mul_f32 v[90:91], v[90:91], v[170:171] op_sel_hi:[1,0]
	v_pk_mul_f32 v[84:85], v[84:85], v[170:171] op_sel_hi:[1,0]
	v_pk_mul_f32 v[86:87], v[86:87], v[170:171] op_sel_hi:[1,0]
	v_pk_mul_f32 v[80:81], v[80:81], v[170:171] op_sel_hi:[1,0]
	v_pk_mul_f32 v[82:83], v[82:83], v[170:171] op_sel_hi:[1,0]
	v_max_f32_e32 v92, 0, v92
	v_max_f32_e32 v93, 0, v93
	v_max_f32_e32 v94, 0, v94
	v_max_f32_e32 v95, 0, v95
	v_max_f32_e32 v88, 0, v88
	v_max_f32_e32 v89, 0, v89
	v_max_f32_e32 v90, 0, v90
	v_max_f32_e32 v91, 0, v91
	v_max_f32_e32 v84, 0, v84
	v_max_f32_e32 v85, 0, v85
	v_max_f32_e32 v86, 0, v86
	v_max_f32_e32 v87, 0, v87
	v_max_f32_e32 v80, 0, v80
	v_max_f32_e32 v81, 0, v81
	v_max_f32_e32 v82, 0, v82
	v_max_f32_e32 v83, 0, v83
	v_pk_mul_f32 v[92:93], v[92:93], v[92:93]
	v_pk_mul_f32 v[94:95], v[94:95], v[94:95]
	v_pk_mul_f32 v[88:89], v[88:89], v[88:89]
	v_pk_mul_f32 v[90:91], v[90:91], v[90:91]
	v_pk_mul_f32 v[84:85], v[84:85], v[84:85]
	v_pk_mul_f32 v[86:87], v[86:87], v[86:87]
	v_pk_mul_f32 v[80:81], v[80:81], v[80:81]
	v_pk_mul_f32 v[82:83], v[82:83], v[82:83]
	v_cvt_pk_bf16_f32 v92, v92, v93
	v_cvt_pk_bf16_f32 v93, v94, v95
	v_cvt_pk_bf16_f32 v94, v88, v89
	v_cvt_pk_bf16_f32 v95, v90, v91
	v_cvt_pk_bf16_f32 v84, v84, v85
	v_cvt_pk_bf16_f32 v85, v86, v87
	v_cvt_pk_bf16_f32 v86, v80, v81
	v_cvt_pk_bf16_f32 v87, v82, v83
	v_add_u32_e32 v225, 0x40000, v224
	v_add_u32_e32 v227, 0x40000, v226
	global_store_dwordx4 v225, v[92:95], s[48:49] sc1
	global_store_dwordx4 v227, v[84:87], s[48:49] sc1
	s_waitcnt vmcnt(10)
	v_fmamk_f32 v172, v172, 0x3a800000, v148
	v_rsq_f32_e32 v172, v172
	s_nop 0
	v_pk_mul_f32 v[76:77], v[76:77], v[172:173] op_sel_hi:[1,0]
	v_pk_mul_f32 v[78:79], v[78:79], v[172:173] op_sel_hi:[1,0]
	v_pk_mul_f32 v[72:73], v[72:73], v[172:173] op_sel_hi:[1,0]
	v_pk_mul_f32 v[74:75], v[74:75], v[172:173] op_sel_hi:[1,0]
	v_pk_mul_f32 v[68:69], v[68:69], v[172:173] op_sel_hi:[1,0]
	v_pk_mul_f32 v[70:71], v[70:71], v[172:173] op_sel_hi:[1,0]
	v_pk_mul_f32 v[64:65], v[64:65], v[172:173] op_sel_hi:[1,0]
	v_pk_mul_f32 v[66:67], v[66:67], v[172:173] op_sel_hi:[1,0]
	v_max_f32_e32 v76, 0, v76
	v_max_f32_e32 v77, 0, v77
	v_max_f32_e32 v78, 0, v78
	v_max_f32_e32 v79, 0, v79
	v_max_f32_e32 v72, 0, v72
	v_max_f32_e32 v73, 0, v73
	v_max_f32_e32 v74, 0, v74
	v_max_f32_e32 v75, 0, v75
	v_max_f32_e32 v68, 0, v68
	v_max_f32_e32 v69, 0, v69
	v_max_f32_e32 v70, 0, v70
	v_max_f32_e32 v71, 0, v71
	v_max_f32_e32 v64, 0, v64
	v_max_f32_e32 v65, 0, v65
	v_max_f32_e32 v66, 0, v66
	v_max_f32_e32 v67, 0, v67
	v_pk_mul_f32 v[76:77], v[76:77], v[76:77]
	v_pk_mul_f32 v[78:79], v[78:79], v[78:79]
	v_pk_mul_f32 v[72:73], v[72:73], v[72:73]
	v_pk_mul_f32 v[74:75], v[74:75], v[74:75]
	v_pk_mul_f32 v[68:69], v[68:69], v[68:69]
	v_pk_mul_f32 v[70:71], v[70:71], v[70:71]
	v_pk_mul_f32 v[64:65], v[64:65], v[64:65]
	v_pk_mul_f32 v[66:67], v[66:67], v[66:67]
	v_cvt_pk_bf16_f32 v76, v76, v77
	v_cvt_pk_bf16_f32 v77, v78, v79
	v_cvt_pk_bf16_f32 v78, v72, v73
	v_cvt_pk_bf16_f32 v79, v74, v75
	v_cvt_pk_bf16_f32 v68, v68, v69
	v_cvt_pk_bf16_f32 v69, v70, v71
	v_cvt_pk_bf16_f32 v70, v64, v65
	v_cvt_pk_bf16_f32 v71, v66, v67
	v_add_u32_e32 v225, 0x60000, v224
	v_add_u32_e32 v227, 0x60000, v226
	global_store_dwordx4 v225, v[76:79], s[48:49] sc1
	global_store_dwordx4 v227, v[68:71], s[48:49] sc1
	s_waitcnt vmcnt(11)
	v_fmamk_f32 v174, v174, 0x3a800000, v148
	v_rsq_f32_e32 v174, v174
	s_nop 0
	v_pk_mul_f32 v[60:61], v[60:61], v[174:175] op_sel_hi:[1,0]
	v_pk_mul_f32 v[62:63], v[62:63], v[174:175] op_sel_hi:[1,0]
	v_pk_mul_f32 v[56:57], v[56:57], v[174:175] op_sel_hi:[1,0]
	v_pk_mul_f32 v[58:59], v[58:59], v[174:175] op_sel_hi:[1,0]
	v_pk_mul_f32 v[52:53], v[52:53], v[174:175] op_sel_hi:[1,0]
	v_pk_mul_f32 v[54:55], v[54:55], v[174:175] op_sel_hi:[1,0]
	v_pk_mul_f32 v[48:49], v[48:49], v[174:175] op_sel_hi:[1,0]
	v_pk_mul_f32 v[50:51], v[50:51], v[174:175] op_sel_hi:[1,0]
	v_max_f32_e32 v60, 0, v60
	v_max_f32_e32 v61, 0, v61
	v_max_f32_e32 v62, 0, v62
	v_max_f32_e32 v63, 0, v63
	v_max_f32_e32 v56, 0, v56
	v_max_f32_e32 v57, 0, v57
	v_max_f32_e32 v58, 0, v58
	v_max_f32_e32 v59, 0, v59
	v_max_f32_e32 v52, 0, v52
	v_max_f32_e32 v53, 0, v53
	v_max_f32_e32 v54, 0, v54
	v_max_f32_e32 v55, 0, v55
	v_max_f32_e32 v48, 0, v48
	v_max_f32_e32 v49, 0, v49
	v_max_f32_e32 v50, 0, v50
	v_max_f32_e32 v51, 0, v51
	v_pk_mul_f32 v[60:61], v[60:61], v[60:61]
	v_pk_mul_f32 v[62:63], v[62:63], v[62:63]
	v_pk_mul_f32 v[56:57], v[56:57], v[56:57]
	v_pk_mul_f32 v[58:59], v[58:59], v[58:59]
	v_pk_mul_f32 v[52:53], v[52:53], v[52:53]
	v_pk_mul_f32 v[54:55], v[54:55], v[54:55]
	v_pk_mul_f32 v[48:49], v[48:49], v[48:49]
	v_pk_mul_f32 v[50:51], v[50:51], v[50:51]
	v_cvt_pk_bf16_f32 v60, v60, v61
	v_cvt_pk_bf16_f32 v61, v62, v63
	v_cvt_pk_bf16_f32 v62, v56, v57
	v_cvt_pk_bf16_f32 v63, v58, v59
	v_cvt_pk_bf16_f32 v52, v52, v53
	v_cvt_pk_bf16_f32 v53, v54, v55
	v_cvt_pk_bf16_f32 v54, v48, v49
	v_cvt_pk_bf16_f32 v55, v50, v51
	v_add_u32_e32 v225, 0x100000, v224
	v_add_u32_e32 v227, 0x100000, v226
	global_store_dwordx4 v225, v[60:63], s[48:49] sc1
	global_store_dwordx4 v227, v[52:55], s[48:49] sc1
	s_waitcnt vmcnt(12)
	v_fmamk_f32 v176, v176, 0x3a800000, v148
	v_rsq_f32_e32 v176, v176
	s_nop 0
	v_pk_mul_f32 v[44:45], v[44:45], v[176:177] op_sel_hi:[1,0]
	v_pk_mul_f32 v[46:47], v[46:47], v[176:177] op_sel_hi:[1,0]
	v_pk_mul_f32 v[40:41], v[40:41], v[176:177] op_sel_hi:[1,0]
	v_pk_mul_f32 v[42:43], v[42:43], v[176:177] op_sel_hi:[1,0]
	v_pk_mul_f32 v[36:37], v[36:37], v[176:177] op_sel_hi:[1,0]
	v_pk_mul_f32 v[38:39], v[38:39], v[176:177] op_sel_hi:[1,0]
	v_pk_mul_f32 v[32:33], v[32:33], v[176:177] op_sel_hi:[1,0]
	v_pk_mul_f32 v[34:35], v[34:35], v[176:177] op_sel_hi:[1,0]
	v_max_f32_e32 v44, 0, v44
	v_max_f32_e32 v45, 0, v45
	v_max_f32_e32 v46, 0, v46
	v_max_f32_e32 v47, 0, v47
	v_max_f32_e32 v40, 0, v40
	v_max_f32_e32 v41, 0, v41
	v_max_f32_e32 v42, 0, v42
	v_max_f32_e32 v43, 0, v43
	v_max_f32_e32 v36, 0, v36
	v_max_f32_e32 v37, 0, v37
	v_max_f32_e32 v38, 0, v38
	v_max_f32_e32 v39, 0, v39
	v_max_f32_e32 v32, 0, v32
	v_max_f32_e32 v33, 0, v33
	v_max_f32_e32 v34, 0, v34
	v_max_f32_e32 v35, 0, v35
	v_pk_mul_f32 v[44:45], v[44:45], v[44:45]
	v_pk_mul_f32 v[46:47], v[46:47], v[46:47]
	v_pk_mul_f32 v[40:41], v[40:41], v[40:41]
	v_pk_mul_f32 v[42:43], v[42:43], v[42:43]
	v_pk_mul_f32 v[36:37], v[36:37], v[36:37]
	v_pk_mul_f32 v[38:39], v[38:39], v[38:39]
	v_pk_mul_f32 v[32:33], v[32:33], v[32:33]
	v_pk_mul_f32 v[34:35], v[34:35], v[34:35]
	v_cvt_pk_bf16_f32 v44, v44, v45
	v_cvt_pk_bf16_f32 v45, v46, v47
	v_cvt_pk_bf16_f32 v46, v40, v41
	v_cvt_pk_bf16_f32 v47, v42, v43
	v_cvt_pk_bf16_f32 v36, v36, v37
	v_cvt_pk_bf16_f32 v37, v38, v39
	v_cvt_pk_bf16_f32 v38, v32, v33
	v_cvt_pk_bf16_f32 v39, v34, v35
	v_add_u32_e32 v225, 0x120000, v224
	v_add_u32_e32 v227, 0x120000, v226
	global_store_dwordx4 v225, v[44:47], s[48:49] sc1
	global_store_dwordx4 v227, v[36:39], s[48:49] sc1
	s_waitcnt vmcnt(13)
	v_fmamk_f32 v178, v178, 0x3a800000, v148
	v_rsq_f32_e32 v178, v178
	s_nop 0
	v_pk_mul_f32 v[28:29], v[28:29], v[178:179] op_sel_hi:[1,0]
	v_pk_mul_f32 v[30:31], v[30:31], v[178:179] op_sel_hi:[1,0]
	v_pk_mul_f32 v[24:25], v[24:25], v[178:179] op_sel_hi:[1,0]
	v_pk_mul_f32 v[26:27], v[26:27], v[178:179] op_sel_hi:[1,0]
	v_pk_mul_f32 v[20:21], v[20:21], v[178:179] op_sel_hi:[1,0]
	v_pk_mul_f32 v[22:23], v[22:23], v[178:179] op_sel_hi:[1,0]
	v_pk_mul_f32 v[16:17], v[16:17], v[178:179] op_sel_hi:[1,0]
	v_pk_mul_f32 v[18:19], v[18:19], v[178:179] op_sel_hi:[1,0]
	v_max_f32_e32 v28, 0, v28
	v_max_f32_e32 v29, 0, v29
	v_max_f32_e32 v30, 0, v30
	v_max_f32_e32 v31, 0, v31
	v_max_f32_e32 v24, 0, v24
	v_max_f32_e32 v25, 0, v25
	v_max_f32_e32 v26, 0, v26
	v_max_f32_e32 v27, 0, v27
	v_max_f32_e32 v20, 0, v20
	v_max_f32_e32 v21, 0, v21
	v_max_f32_e32 v22, 0, v22
	v_max_f32_e32 v23, 0, v23
	v_max_f32_e32 v16, 0, v16
	v_max_f32_e32 v17, 0, v17
	v_max_f32_e32 v18, 0, v18
	v_max_f32_e32 v19, 0, v19
	v_pk_mul_f32 v[28:29], v[28:29], v[28:29]
	v_pk_mul_f32 v[30:31], v[30:31], v[30:31]
	v_pk_mul_f32 v[24:25], v[24:25], v[24:25]
	v_pk_mul_f32 v[26:27], v[26:27], v[26:27]
	v_pk_mul_f32 v[20:21], v[20:21], v[20:21]
	v_pk_mul_f32 v[22:23], v[22:23], v[22:23]
	v_pk_mul_f32 v[16:17], v[16:17], v[16:17]
	v_pk_mul_f32 v[18:19], v[18:19], v[18:19]
	v_cvt_pk_bf16_f32 v28, v28, v29
	v_cvt_pk_bf16_f32 v29, v30, v31
	v_cvt_pk_bf16_f32 v30, v24, v25
	v_cvt_pk_bf16_f32 v31, v26, v27
	v_cvt_pk_bf16_f32 v20, v20, v21
	v_cvt_pk_bf16_f32 v21, v22, v23
	v_cvt_pk_bf16_f32 v22, v16, v17
	v_cvt_pk_bf16_f32 v23, v18, v19
	v_add_u32_e32 v225, 0x140000, v224
	v_add_u32_e32 v227, 0x140000, v226
	global_store_dwordx4 v225, v[28:31], s[48:49] sc1
	global_store_dwordx4 v227, v[20:23], s[48:49] sc1
	s_waitcnt vmcnt(14)
	v_fmamk_f32 v180, v180, 0x3a800000, v148
	v_rsq_f32_e32 v180, v180
	s_nop 0
	v_pk_mul_f32 v[12:13], v[12:13], v[180:181] op_sel_hi:[1,0]
	v_pk_mul_f32 v[14:15], v[14:15], v[180:181] op_sel_hi:[1,0]
	v_pk_mul_f32 v[8:9], v[8:9], v[180:181] op_sel_hi:[1,0]
	v_pk_mul_f32 v[10:11], v[10:11], v[180:181] op_sel_hi:[1,0]
	v_pk_mul_f32 v[4:5], v[4:5], v[180:181] op_sel_hi:[1,0]
	v_pk_mul_f32 v[6:7], v[6:7], v[180:181] op_sel_hi:[1,0]
	v_pk_mul_f32 v[0:1], v[0:1], v[180:181] op_sel_hi:[1,0]
	v_pk_mul_f32 v[2:3], v[2:3], v[180:181] op_sel_hi:[1,0]
	v_max_f32_e32 v12, 0, v12
	v_max_f32_e32 v13, 0, v13
	v_max_f32_e32 v14, 0, v14
	v_max_f32_e32 v15, 0, v15
	v_max_f32_e32 v8, 0, v8
	v_max_f32_e32 v9, 0, v9
	v_max_f32_e32 v10, 0, v10
	v_max_f32_e32 v11, 0, v11
	v_max_f32_e32 v4, 0, v4
	v_max_f32_e32 v5, 0, v5
	v_max_f32_e32 v6, 0, v6
	v_max_f32_e32 v7, 0, v7
	v_max_f32_e32 v0, 0, v0
	v_max_f32_e32 v1, 0, v1
	v_max_f32_e32 v2, 0, v2
	v_max_f32_e32 v3, 0, v3
	v_pk_mul_f32 v[12:13], v[12:13], v[12:13]
	v_pk_mul_f32 v[14:15], v[14:15], v[14:15]
	v_pk_mul_f32 v[8:9], v[8:9], v[8:9]
	v_pk_mul_f32 v[10:11], v[10:11], v[10:11]
	v_pk_mul_f32 v[4:5], v[4:5], v[4:5]
	v_pk_mul_f32 v[6:7], v[6:7], v[6:7]
	v_pk_mul_f32 v[0:1], v[0:1], v[0:1]
	v_pk_mul_f32 v[2:3], v[2:3], v[2:3]
	v_cvt_pk_bf16_f32 v12, v12, v13
	v_cvt_pk_bf16_f32 v13, v14, v15
	v_cvt_pk_bf16_f32 v14, v8, v9
	v_cvt_pk_bf16_f32 v15, v10, v11
	v_cvt_pk_bf16_f32 v4, v4, v5
	v_cvt_pk_bf16_f32 v5, v6, v7
	v_cvt_pk_bf16_f32 v6, v0, v1
	v_cvt_pk_bf16_f32 v7, v2, v3
	v_add_u32_e32 v225, 0x160000, v224
	v_add_u32_e32 v227, 0x160000, v226
	global_store_dwordx4 v225, v[12:15], s[48:49] sc1
	global_store_dwordx4 v227, v[4:7], s[48:49] sc1
	s_mov_b32 s11, 0x160000
	s_andn2_b64 vcc, exec, s[36:37]
	s_mov_b64 s[14:15], -1
	s_cbranch_vccnz .LBB0_656
	s_andn2_b64 vcc, exec, s[4:5]
	s_cbranch_vccnz .LBB0_655
	s_barrier
	s_branch .LBB0_655
